# recurrence loader loads non-temporal (read-once Q/KK/V/P/gate chunks)
# baseline (speedup 1.0000x reference)
; #define LBAR() do { asm volatile("s_waitcnt lgkmcnt(0)" ::: "memory"); __builtin_amdgcn_s_barrier(); asm volatile("" ::: "memory"); } while (0)
; #define GATE_LOAD(cc) do { _Pragma("unroll") for (int jj = 0; jj < 4; ++jj) gt[jj] = *(const v4u*)(Y + ((size_t)b * SEQL + 64 * (cc) + ((lt + 256 * jj) >> 4)) * 1024 + (size_t)h * 128 + 8 * foct); } while (0)
; __device__ __forceinline__ void hgrn_unit(LAS unsigned char* lds, int b, int h, const bf16* Q, const bf16* KK, const bf16* V, const bf16* PBUF, const float* DBUF, bf16* Y, const float* onw) {
;     ...
;         const int foct = lt & 15;
;         const f32x4 fw0 = *(const f32x4*)(onw + 8 * foct), fw1 = *(const f32x4*)(onw + 8 * foct + 4);
;         v4u gt[4];
;     ...
;         LD_ISSUE(0, lqA, lkA, lvA, lpA, ldA);
;         LD_WRITE(0, lqA, lkA, lvA, lpA, ldA); LD_ISSUE(1, lqA, lkA, lvA, lpA, ldA);
;         GATE_LOAD(0);
;         LBAR();
.LBB0_1286:
	s_or_b64 exec, exec, s[10:11]
	s_movk_i32 s9, 0x88
	v_mad_u64_u32 v[102:103], s[10:11], v92, s9, v[96:97]
	v_lshl_add_u32 v72, v102, 1, 0
	v_mad_u64_u32 v[104:105], s[10:11], v90, s9, v[96:97]
	s_waitcnt vmcnt(13)
	ds_write_b128 v72, v[10:13]
	s_waitcnt vmcnt(12)
	ds_write_b128 v72, v[14:17] offset:17408
	s_waitcnt vmcnt(11)
	ds_write_b128 v72, v[22:25] offset:34816
	v_lshl_add_u32 v10, v104, 1, 0
	v_mad_u64_u32 v[106:107], s[10:11], v88, s9, v[96:97]
	s_waitcnt vmcnt(10)
	ds_write_b128 v10, v[18:21]
	s_waitcnt vmcnt(9)
	ds_write_b128 v10, v[26:29] offset:17408
	s_waitcnt vmcnt(8)
	ds_write_b128 v10, v[30:33] offset:34816
	v_lshl_add_u32 v10, v106, 1, 0
	v_mad_u64_u32 v[108:109], s[10:11], v86, s9, v[96:97]
	s_waitcnt vmcnt(7)
	ds_write_b128 v10, v[34:37]
	s_waitcnt vmcnt(6)
	ds_write_b128 v10, v[38:41] offset:17408
	s_waitcnt vmcnt(5)
	ds_write_b128 v10, v[46:49] offset:34816
	v_lshl_add_u32 v10, v108, 1, 0
	v_and_b32_e32 v109, 56, v71
	v_lshrrev_b32_e32 v11, 3, v97
	s_waitcnt vmcnt(4)
	ds_write_b128 v10, v[42:45]
	s_waitcnt vmcnt(3)
	ds_write_b128 v10, v[50:53] offset:17408
	s_waitcnt vmcnt(2)
	ds_write_b128 v10, v[54:57] offset:34816
	v_lshl_add_u32 v10, v109, 1, 0
	v_mul_lo_u32 v130, v11, s91
	v_add_u32_e32 v11, v10, v130
	s_waitcnt vmcnt(1)
	ds_write_b128 v11, v[62:65] offset:52224
	v_lshrrev_b32_e32 v11, 3, v1
	v_mul_lo_u32 v131, v11, s91
	v_add_u32_e32 v10, v10, v131
	s_waitcnt vmcnt(0)
	ds_write_b128 v10, v[58:61] offset:52224
	s_and_saveexec_b64 s[10:11], s[0:1]
	v_lshl_add_u32 v10, v97, 4, 0
	ds_write_b128 v10, v[66:69] offset:61440
	s_or_b64 exec, exec, s[10:11]
	s_or_b32 s10, s2, 64
	s_mov_b32 s11, s3
	v_lshl_add_u64 v[10:11], s[10:11], 0, v[92:93]
	v_lshlrev_b64 v[10:11], 11, v[10:11]
	v_or_b32_e32 v10, v10, v70
	v_readlane_b32 s20, v253, 0
	v_lshl_add_u64 v[12:13], s[34:35], 0, v[10:11]
	v_readlane_b32 s21, v253, 1
	v_readlane_b32 s22, v253, 13
	v_readlane_b32 s23, v253, 14
	v_lshl_add_u64 v[14:15], s[20:21], 0, v[10:11]
	global_load_dwordx4 v[18:21], v[12:13], off nt
	global_load_dwordx4 v[22:25], v[14:15], off nt
	v_lshl_add_u64 v[12:13], s[10:11], 0, v[90:91]
	v_lshlrev_b64 v[12:13], 11, v[12:13]
	v_lshl_add_u64 v[10:11], s[22:23], 0, v[10:11]
	v_or_b32_e32 v12, v12, v70
	v_lshl_add_u64 v[14:15], s[34:35], 0, v[12:13]
	global_load_dwordx4 v[26:29], v[10:11], off nt
	global_load_dwordx4 v[30:33], v[14:15], off nt
	v_lshl_add_u64 v[10:11], s[20:21], 0, v[12:13]
	v_lshl_add_u64 v[12:13], s[22:23], 0, v[12:13]
	global_load_dwordx4 v[34:37], v[10:11], off nt
	global_load_dwordx4 v[38:41], v[12:13], off nt
	v_lshl_add_u64 v[10:11], s[10:11], 0, v[88:89]
	v_lshlrev_b64 v[10:11], 11, v[10:11]
	v_or_b32_e32 v10, v10, v70
	v_lshl_add_u64 v[12:13], s[34:35], 0, v[10:11]
	s_or_b32 s8, s8, 1
	v_lshl_add_u64 v[14:15], s[20:21], 0, v[10:11]
	global_load_dwordx4 v[42:45], v[12:13], off nt
	global_load_dwordx4 v[46:49], v[14:15], off nt
	v_lshl_add_u64 v[12:13], s[10:11], 0, v[86:87]
	s_ashr_i32 s9, s8, 31
	v_lshlrev_b64 v[12:13], 11, v[12:13]
	s_lshl_b64 s[10:11], s[8:9], 13
	v_lshl_add_u64 v[10:11], s[22:23], 0, v[10:11]
	v_or_b32_e32 v12, v12, v70
	s_add_u32 s10, s80, s10
	v_lshl_add_u64 v[14:15], s[34:35], 0, v[12:13]
	global_load_dwordx4 v[50:53], v[10:11], off nt
	global_load_dwordx4 v[54:57], v[14:15], off nt
	v_lshl_add_u64 v[10:11], s[20:21], 0, v[12:13]
	s_addc_u32 s11, s81, s11
	v_lshl_add_u64 v[12:13], s[22:23], 0, v[12:13]
	global_load_dwordx4 v[58:61], v[10:11], off nt
	global_load_dwordx4 v[62:65], v[12:13], off nt
	v_lshl_add_u64 v[10:11], v[98:99], 1, s[10:11]
	v_lshl_add_u64 v[12:13], v[100:101], 1, s[10:11]
	global_load_dwordx4 v[70:73], v[10:11], off nt
	global_load_dwordx4 v[74:77], v[12:13], off nt
	s_and_saveexec_b64 s[10:11], vcc
	s_xor_b64 s[10:11], exec, s[10:11]
	v_mov_b32_e32 v115, v0
	s_or_saveexec_b64 s[10:11], s[10:11]
	v_mov_b32_e32 v78, 0
	v_mov_b32_e32 v79, 0
	v_mov_b32_e32 v80, 0
	v_mov_b32_e32 v81, 0
	s_xor_b64 exec, exec, s[10:11]
	s_cbranch_execz .LBB0_1292
	s_lshl_b64 s[8:9], s[8:9], 9
	v_readlane_b32 s20, v252, 39
	v_readlane_b32 s21, v252, 40
	s_add_u32 s8, s20, s8
	s_addc_u32 s9, s21, s9
	v_lshl_add_u64 v[10:11], v[114:115], 2, s[8:9]
	global_load_dwordx4 v[78:81], v[10:11], off nt
.LBB0_1292:
	s_or_b64 exec, exec, s[10:11]
	s_and_b32 s8, s12, 7
	s_lshl_b32 s10, s8, 5
	s_lshl_b32 s11, s8, 8
	s_lshl_b32 s26, s18, 1
	s_add_u32 s8, s50, s26
	s_addc_u32 s9, s51, 0
	v_lshlrev_b32_e32 v116, 1, v96
	v_mov_b32_e32 v117, v0
	v_lshl_add_u64 v[94:95], s[8:9], 0, v[116:117]
	v_lshl_add_u64 v[10:11], v[94:95], 0, v[82:83]
	v_lshl_add_u64 v[12:13], v[94:95], 0, v[84:85]
	global_load_dwordx4 v[82:85], v[10:11], off nt
	global_load_dwordx4 v[66:69], v[12:13], off nt
	v_lshl_add_u64 v[10:11], v[94:95], 0, v[110:111]
	v_lshl_add_u64 v[12:13], v[94:95], 0, v[112:113]
	global_load_dwordx4 v[14:17], v[10:11], off nt
	s_nop 0
	global_load_dwordx4 v[10:13], v[12:13], off nt
	v_readlane_b32 s8, v254, 62
	v_lshl_add_u64 v[110:111], s[50:51], 0, v[116:117]
	s_lshl_b64 s[6:7], s[6:7], 22
	v_add_u32_e32 v135, s8, v116
	v_readlane_b32 s8, v252, 39
	v_readlane_b32 s9, v252, 40
	v_or_b32_e32 v147, s11, v116
	v_lshlrev_b64 v[116:117], 11, v[88:89]
	v_lshl_add_u64 v[112:113], v[114:115], 2, s[8:9]
	v_lshlrev_b64 v[114:115], 11, v[86:87]
	v_lshlrev_b64 v[118:119], 11, v[90:91]
	v_lshlrev_b64 v[120:121], 11, v[92:93]
	v_lshl_add_u64 v[122:123], s[6:7], 0, v[114:115]
	v_lshl_add_u64 v[124:125], s[6:7], 0, v[116:117]
	v_lshl_add_u64 v[126:127], s[6:7], 0, v[118:119]
	v_lshl_add_u64 v[128:129], s[6:7], 0, v[120:121]
	v_or_b32_e32 v114, v122, v147
	v_or_b32_e32 v116, v124, v147
	v_or_b32_e32 v118, v126, v147
	v_or_b32_e32 v120, v128, v147
	v_lshlrev_b32_e32 v147, 4, v1
	s_waitcnt lgkmcnt(0)
	s_barrier
	v_and_b32_e32 v147, 0xf0, v147
	s_movk_i32 s8, 0x110
	s_add_i32 s15, s15, s10
	v_mov_b32_e32 v115, v123
	v_mov_b32_e32 v117, v125
	v_mov_b32_e32 v119, v127
	v_mov_b32_e32 v121, v129
	v_or3_b32 v122, v122, s11, v147
	v_or3_b32 v124, v124, s11, v147
	v_or3_b32 v126, v126, s11, v147
	v_or3_b32 v128, v128, s11, v147
	v_lshl_add_u64 v[110:111], v[110:111], 0, s[26:27]
	v_lshlrev_b32_e32 v137, 4, v97
	v_lshlrev_b32_e32 v136, 5, v92
	v_mul_lo_u32 v134, v92, s8
	v_lshlrev_b32_e32 v133, 5, v90
	v_mul_lo_u32 v132, v90, s8
	v_lshlrev_b32_e32 v107, 5, v88
	v_mul_lo_u32 v105, v88, s8
	v_lshlrev_b32_e32 v103, 5, v86
	v_mul_lo_u32 v97, v86, s8
	s_add_i32 s15, s15, 2
	v_lshl_add_u64 v[114:115], s[82:83], 0, v[114:115]
	v_lshl_add_u64 v[116:117], s[82:83], 0, v[116:117]
	v_lshl_add_u64 v[118:119], s[82:83], 0, v[118:119]
	v_lshl_add_u64 v[120:121], s[82:83], 0, v[120:121]
	v_lshl_add_u64 v[122:123], s[50:51], 0, v[122:123]
	v_lshl_add_u64 v[124:125], s[50:51], 0, v[124:125]
	v_lshl_add_u64 v[126:127], s[50:51], 0, v[126:127]
	v_lshl_add_u64 v[128:129], s[50:51], 0, v[128:129]
	s_mov_b32 s10, 0
	s_mov_b64 s[6:7], 0
	s_movk_i32 s18, 0xffc0
	s_mov_b32 s20, s85
	s_mov_b32 s21, 0x100000
	s_waitcnt vmcnt(4)
	s_cmp_eq_u32 s6, 0
	s_cbranch_scc1 .LBB0_1294
.LBB0_1293:
	s_add_i32 s8, s10, -1
	s_and_b32 s8, s8, 1
	s_lshl_b32 s9, s8, 11
	s_add_i32 s11, s9, 0
	s_add_i32 s11, s11, 0x1e400
	v_add_u32_e32 v147, s11, v136
	ds_read_b128 v[150:153], v147
	ds_read_b128 v[154:157], v147 offset:16
	s_mulk_i32 s8, 0x4400
	v_add_u32_e32 v147, s8, v135
	v_add_u32_e32 v177, s11, v133
	s_waitcnt lgkmcnt(1)
	v_mov_b32_e32 v158, v150
	s_waitcnt lgkmcnt(0)
	v_mov_b32_e32 v159, v154
	v_mov_b32_e32 v154, v151
	v_add_u32_e32 v150, v147, v134
	v_pk_add_f32 v[154:155], v[158:159], v[154:155]
	v_mov_b32_e32 v158, v152
	v_mov_b32_e32 v159, v156
	v_mov_b32_e32 v156, v153
	ds_read_b128 v[150:153], v150
	v_pk_add_f32 v[156:157], v[158:159], v[156:157]
	s_mov_b32 s22, 0x358637bd
	v_pk_add_f32 v[158:159], v[154:155], v[156:157]
	ds_read_b128 v[154:157], v177
	s_waitcnt lgkmcnt(1)
	v_lshlrev_b32_e32 v162, 16, v150
	v_and_b32_e32 v163, 0xffff0000, v150
	v_lshlrev_b32_e32 v166, 16, v151
	v_and_b32_e32 v167, 0xffff0000, v151
	v_lshlrev_b32_e32 v170, 16, v152
	v_and_b32_e32 v171, 0xffff0000, v152
	v_lshlrev_b32_e32 v174, 16, v153
	v_and_b32_e32 v175, 0xffff0000, v153
	ds_read_b128 v[150:153], v177 offset:16
	s_waitcnt lgkmcnt(1)
	v_mov_b32_e32 v178, v154
	v_mov_b32_e32 v154, v156
	s_add_u32 s8, s2, s18
	s_addc_u32 s9, s3, 0
	s_waitcnt lgkmcnt(0)
	v_mov_b32_e32 v179, v150
	v_mov_b32_e32 v150, v155
	v_mov_b32_e32 v155, v152
	v_mov_b32_e32 v152, v157
	v_pk_add_f32 v[150:151], v[178:179], v[150:151]
	v_pk_add_f32 v[152:153], v[154:155], v[152:153]
	v_mov_b64_e32 v[154:155], s[22:23]
	v_pk_add_f32 v[150:151], v[150:151], v[152:153]
	v_mov_b32_e32 v153, v158
	v_mov_b32_e32 v152, v150
	v_mov_b32_e32 v158, v151
	v_pk_add_f32 v[150:151], v[152:153], v[158:159]
	s_brev_b32 s22, 60
	v_pk_fma_f32 v[156:157], v[150:151], s[22:23], v[154:155] op_sel_hi:[1,0,0]
	s_waitcnt vmcnt(17)
	v_lshlrev_b32_e32 v164, 16, v82
	v_and_b32_e32 v165, 0xffff0000, v82
	v_lshlrev_b32_e32 v168, 16, v83
	v_mov_b32_e32 v150, v157
	v_rsq_f32_e32 v152, v150
	v_lshl_add_u64 v[150:151], s[8:9], 0, v[92:93]
	v_lshlrev_b64 v[150:151], 11, v[150:151]
	v_lshl_add_u64 v[158:159], v[110:111], 0, v[150:151]
	s_nop 0
	v_mov_b32_e32 v178, v152
	v_pk_mul_f32 v[150:151], v[178:179], v[162:163] op_sel_hi:[0,1]
	v_pk_mul_f32 v[152:153], v[178:179], v[166:167] op_sel_hi:[0,1]
	v_and_b32_e32 v169, 0xffff0000, v83
	v_pk_mul_f32 v[150:151], v[6:7], v[150:151]
	v_pk_mul_f32 v[152:153], v[8:9], v[152:153]
	v_pk_mul_f32 v[150:151], v[150:151], v[164:165]
	v_pk_mul_f32 v[152:153], v[152:153], v[168:169]
	v_cvt_pk_bf16_f32 v150, v150, v151
	v_cvt_pk_bf16_f32 v151, v152, v153
	v_pk_mul_f32 v[152:153], v[178:179], v[170:171] op_sel_hi:[0,1]
	v_lshlrev_b32_e32 v172, 16, v84
	v_and_b32_e32 v173, 0xffff0000, v84
	v_pk_mul_f32 v[152:153], v[2:3], v[152:153]
	v_pk_mul_f32 v[152:153], v[152:153], v[172:173]
	v_add_u32_e32 v82, v147, v132
	v_cvt_pk_bf16_f32 v152, v152, v153
	v_mov_b32_e32 v153, v156
	v_lshlrev_b32_e32 v176, 16, v85
	v_and_b32_e32 v177, 0xffff0000, v85
	ds_read_b128 v[82:85], v82
	v_pk_mul_f32 v[162:163], v[178:179], v[174:175] op_sel_hi:[0,1]
	v_rsq_f32_e32 v164, v153
	v_pk_mul_f32 v[162:163], v[4:5], v[162:163]
	v_add_u32_e32 v171, s11, v103
	v_pk_mul_f32 v[156:157], v[162:163], v[176:177]
	s_waitcnt vmcnt(15)
	v_lshlrev_b32_e32 v162, 16, v15
	v_cvt_pk_bf16_f32 v153, v156, v157
	global_store_dwordx4 v[158:159], v[150:153], off
	v_lshlrev_b32_e32 v156, 16, v66
	v_and_b32_e32 v157, 0xffff0000, v66
	s_nop 0
	v_mov_b32_e32 v150, v164
	s_waitcnt lgkmcnt(0)
	v_lshlrev_b32_e32 v152, 16, v82
	v_and_b32_e32 v153, 0xffff0000, v82
	v_pk_mul_f32 v[152:153], v[150:151], v[152:153] op_sel_hi:[0,1]
	v_pk_mul_f32 v[152:153], v[6:7], v[152:153]
	v_lshlrev_b32_e32 v82, 16, v83
	v_and_b32_e32 v83, 0xffff0000, v83
	v_pk_mul_f32 v[152:153], v[152:153], v[156:157]
	v_pk_mul_f32 v[82:83], v[150:151], v[82:83] op_sel_hi:[0,1]
	v_cvt_pk_bf16_f32 v66, v152, v153
	v_pk_mul_f32 v[82:83], v[8:9], v[82:83]
	v_lshlrev_b32_e32 v152, 16, v67
	v_and_b32_e32 v153, 0xffff0000, v67
	v_pk_mul_f32 v[82:83], v[82:83], v[152:153]
	v_lshlrev_b32_e32 v152, 16, v68
	v_cvt_pk_bf16_f32 v67, v82, v83
	v_lshlrev_b32_e32 v82, 16, v84
	v_and_b32_e32 v83, 0xffff0000, v84
	v_pk_mul_f32 v[82:83], v[150:151], v[82:83] op_sel_hi:[0,1]
	v_pk_mul_f32 v[82:83], v[2:3], v[82:83]
	v_and_b32_e32 v153, 0xffff0000, v68
	v_pk_mul_f32 v[82:83], v[82:83], v[152:153]
	v_lshlrev_b32_e32 v84, 16, v69
	v_cvt_pk_bf16_f32 v68, v82, v83
	v_lshlrev_b32_e32 v82, 16, v85
	v_and_b32_e32 v83, 0xffff0000, v85
	v_pk_mul_f32 v[82:83], v[150:151], v[82:83] op_sel_hi:[0,1]
	v_pk_mul_f32 v[82:83], v[4:5], v[82:83]
	v_and_b32_e32 v85, 0xffff0000, v69
	v_pk_mul_f32 v[82:83], v[82:83], v[84:85]
	v_add_u32_e32 v150, s11, v107
	v_cvt_pk_bf16_f32 v69, v82, v83
	ds_read_b128 v[82:85], v150
	ds_read_b128 v[150:153], v150 offset:16
	v_lshl_add_u64 v[156:157], s[8:9], 0, v[90:91]
	v_lshlrev_b64 v[156:157], 11, v[156:157]
	v_lshl_add_u64 v[156:157], v[110:111], 0, v[156:157]
	global_store_dwordx4 v[156:157], v[66:69], off
	v_lshlrev_b32_e32 v156, 16, v14
	v_and_b32_e32 v157, 0xffff0000, v14
	s_waitcnt lgkmcnt(1)
	v_mov_b32_e32 v66, v82
	s_waitcnt lgkmcnt(0)
	v_mov_b32_e32 v67, v150
	v_mov_b32_e32 v150, v83
	v_pk_add_f32 v[82:83], v[66:67], v[150:151]
	v_add_u32_e32 v66, v147, v105
	ds_read_b128 v[66:69], v66
	v_mov_b32_e32 v150, v84
	v_mov_b32_e32 v151, v152
	v_mov_b32_e32 v152, v85
	v_pk_add_f32 v[84:85], v[150:151], v[152:153]
	v_and_b32_e32 v163, 0xffff0000, v15
	v_pk_add_f32 v[150:151], v[82:83], v[84:85]
	ds_read_b128 v[82:85], v171
	s_waitcnt lgkmcnt(1)
; #define LBAR() do { asm volatile("s_waitcnt lgkmcnt(0)" ::: "memory"); __builtin_amdgcn_s_barrier(); asm volatile("" ::: "memory"); } while (0)
; #define GATE_LOAD(cc) do { _Pragma("unroll") for (int jj = 0; jj < 4; ++jj) gt[jj] = *(const v4u*)(Y + ((size_t)b * SEQL + 64 * (cc) + ((lt + 256 * jj) >> 4)) * 1024 + (size_t)h * 128 + 8 * foct); } while (0)
; __device__ __forceinline__ void hgrn_unit(LAS unsigned char* lds, int b, int h, const bf16* Q, const bf16* KK, const bf16* V, const bf16* PBUF, const float* DBUF, bf16* Y, const float* onw) {
;     ...
;         LD_ISSUE(0, lqA, lkA, lvA, lpA, ldA);
;         LD_WRITE(0, lqA, lkA, lvA, lpA, ldA); LD_ISSUE(1, lqA, lkA, lvA, lpA, ldA);
;         GATE_LOAD(0);
;         LBAR();
; #pragma unroll 1
;         for (int c = 0; c < 32; ++c) {
;             if (c > 0) { FINISH(c - 1); GATE_LOAD(c); }
	v_lshlrev_b32_e32 v152, 16, v66
	v_and_b32_e32 v153, 0xffff0000, v66
	v_lshlrev_b32_e32 v158, 16, v67
	v_and_b32_e32 v159, 0xffff0000, v67
	v_lshlrev_b32_e32 v164, 16, v68
	v_and_b32_e32 v165, 0xffff0000, v68
	v_lshlrev_b32_e32 v168, 16, v69
	v_and_b32_e32 v169, 0xffff0000, v69
	ds_read_b128 v[66:69], v171 offset:16
	s_waitcnt lgkmcnt(1)
	v_mov_b32_e32 v172, v82
	v_mov_b32_e32 v82, v84
	v_lshlrev_b32_e32 v166, 16, v16
	v_and_b32_e32 v167, 0xffff0000, v16
	s_waitcnt lgkmcnt(0)
	v_mov_b32_e32 v173, v66
	v_mov_b32_e32 v66, v83
	v_mov_b32_e32 v83, v68
	v_mov_b32_e32 v68, v85
	v_pk_add_f32 v[66:67], v[172:173], v[66:67]
	v_pk_add_f32 v[68:69], v[82:83], v[68:69]
	v_add_u32_e32 v14, v147, v97
	v_pk_add_f32 v[66:67], v[66:67], v[68:69]
	v_mov_b32_e32 v69, v150
	v_mov_b32_e32 v68, v66
	v_mov_b32_e32 v150, v67
	v_pk_add_f32 v[66:67], v[68:69], v[150:151]
	v_lshlrev_b32_e32 v170, 16, v17
	v_pk_fma_f32 v[82:83], v[66:67], s[22:23], v[154:155] op_sel_hi:[1,0,0]
	v_and_b32_e32 v171, 0xffff0000, v17
	ds_read_b128 v[14:17], v14
	s_nop 0
	v_mov_b32_e32 v66, v83
	v_rsq_f32_e32 v68, v66
	v_lshl_add_u64 v[66:67], s[8:9], 0, v[88:89]
	v_lshlrev_b64 v[66:67], 11, v[66:67]
	v_lshl_add_u64 v[84:85], v[110:111], 0, v[66:67]
	s_nop 0
	v_mov_b32_e32 v150, v68
	v_pk_mul_f32 v[66:67], v[150:151], v[152:153] op_sel_hi:[0,1]
	v_pk_mul_f32 v[68:69], v[150:151], v[158:159] op_sel_hi:[0,1]
	v_pk_mul_f32 v[66:67], v[6:7], v[66:67]
	v_pk_mul_f32 v[68:69], v[8:9], v[68:69]
	v_pk_mul_f32 v[66:67], v[66:67], v[156:157]
	v_pk_mul_f32 v[68:69], v[68:69], v[162:163]
	v_cvt_pk_bf16_f32 v66, v66, v67
	v_cvt_pk_bf16_f32 v67, v68, v69
	v_pk_mul_f32 v[68:69], v[150:151], v[164:165] op_sel_hi:[0,1]
	v_pk_mul_f32 v[68:69], v[2:3], v[68:69]
	v_pk_mul_f32 v[68:69], v[68:69], v[166:167]
	v_pk_mul_f32 v[150:151], v[150:151], v[168:169] op_sel_hi:[0,1]
	v_cvt_pk_bf16_f32 v68, v68, v69
	v_mov_b32_e32 v69, v82
	v_rsq_f32_e32 v147, v69
	v_pk_mul_f32 v[150:151], v[4:5], v[150:151]
	s_nop 0
	v_pk_mul_f32 v[82:83], v[150:151], v[170:171]
	s_nop 0
	v_cvt_pk_bf16_f32 v69, v82, v83
	global_store_dwordx4 v[84:85], v[66:69], off
	s_waitcnt vmcnt(17)
	v_lshlrev_b32_e32 v82, 16, v10
	v_and_b32_e32 v83, 0xffff0000, v10
	s_nop 0
	v_mov_b32_e32 v66, v147
	s_waitcnt lgkmcnt(0)
	v_lshlrev_b32_e32 v68, 16, v14
	v_and_b32_e32 v69, 0xffff0000, v14
	v_pk_mul_f32 v[68:69], v[66:67], v[68:69] op_sel_hi:[0,1]
	v_pk_mul_f32 v[68:69], v[6:7], v[68:69]
	v_lshlrev_b32_e32 v14, 16, v15
	v_and_b32_e32 v15, 0xffff0000, v15
	v_pk_mul_f32 v[68:69], v[68:69], v[82:83]
	v_pk_mul_f32 v[14:15], v[66:67], v[14:15] op_sel_hi:[0,1]
	v_cvt_pk_bf16_f32 v10, v68, v69
	v_pk_mul_f32 v[14:15], v[8:9], v[14:15]
	v_lshlrev_b32_e32 v68, 16, v11
	v_and_b32_e32 v69, 0xffff0000, v11
	v_pk_mul_f32 v[14:15], v[14:15], v[68:69]
	v_lshlrev_b32_e32 v68, 16, v12
	v_cvt_pk_bf16_f32 v11, v14, v15
	v_lshlrev_b32_e32 v14, 16, v16
	v_and_b32_e32 v15, 0xffff0000, v16
	v_pk_mul_f32 v[14:15], v[66:67], v[14:15] op_sel_hi:[0,1]
	v_pk_mul_f32 v[14:15], v[2:3], v[14:15]
	v_and_b32_e32 v69, 0xffff0000, v12
	v_pk_mul_f32 v[14:15], v[14:15], v[68:69]
	v_lshlrev_b32_e32 v16, 16, v13
	v_cvt_pk_bf16_f32 v12, v14, v15
	v_lshlrev_b32_e32 v14, 16, v17
	v_and_b32_e32 v15, 0xffff0000, v17
	v_pk_mul_f32 v[14:15], v[66:67], v[14:15] op_sel_hi:[0,1]
	v_pk_mul_f32 v[14:15], v[4:5], v[14:15]
	v_and_b32_e32 v17, 0xffff0000, v13
	v_pk_mul_f32 v[14:15], v[14:15], v[16:17]
	s_nop 0
	v_cvt_pk_bf16_f32 v13, v14, v15
	v_lshl_add_u64 v[14:15], s[8:9], 0, v[86:87]
	v_lshlrev_b64 v[14:15], 11, v[14:15]
	v_lshl_add_u64 v[14:15], v[110:111], 0, v[14:15]
	global_store_dwordx4 v[14:15], v[10:13], off
	s_nop 1
	v_lshl_add_u64 v[10:11], v[128:129], 0, s[6:7]
	v_lshl_add_u64 v[12:13], v[126:127], 0, s[6:7]
	global_load_dwordx4 v[82:85], v[10:11], off nt
	global_load_dwordx4 v[66:69], v[12:13], off nt
	v_lshl_add_u64 v[10:11], v[124:125], 0, s[6:7]
	v_lshl_add_u64 v[12:13], v[122:123], 0, s[6:7]
	global_load_dwordx4 v[14:17], v[10:11], off nt
	s_nop 0
	global_load_dwordx4 v[10:13], v[12:13], off nt
; #define GATE_LOAD(cc) do { _Pragma("unroll") for (int jj = 0; jj < 4; ++jj) gt[jj] = *(const v4u*)(Y + ((size_t)b * SEQL + 64 * (cc) + ((lt + 256 * jj) >> 4)) * 1024 + (size_t)h * 128 + 8 * foct); } while (0)
; __device__ __forceinline__ void hgrn_unit(LAS unsigned char* lds, int b, int h, const bf16* Q, const bf16* KK, const bf16* V, const bf16* PBUF, const float* DBUF, bf16* Y, const float* onw) {
;     ...
;         for (int c = 0; c < 32; ++c) {
;             if (c > 0) { FINISH(c - 1); GATE_LOAD(c); }
;             if (c + 1 < 32) { LD_WRITE((c + 1) & 1, lqA, lkA, lvA, lpA, ldA); if (c + 2 < 32) LD_ISSUE(c + 2, lqA, lkA, lvA, lpA, ldA); }
.LBB0_1294:
	s_add_i32 s19, s10, 1
	s_cmp_eq_u32 s6, 0x3e0000
	s_cbranch_scc1 .LBB0_1302
	s_bitcmp1_b32 s19, 0
	s_cselect_b32 s8, 0xf200, 0
	s_add_i32 s11, s8, 0
	v_lshl_add_u32 v147, v102, 1, s11
	s_waitcnt vmcnt(21)
	ds_write_b128 v147, v[18:21]
	s_waitcnt vmcnt(20)
	ds_write_b128 v147, v[22:25] offset:17408
	s_waitcnt vmcnt(19)
	ds_write_b128 v147, v[26:29] offset:34816
	v_lshl_add_u32 v147, v104, 1, s11
	s_waitcnt vmcnt(18)
	ds_write_b128 v147, v[30:33]
	s_waitcnt vmcnt(17)
	ds_write_b128 v147, v[34:37] offset:17408
	s_waitcnt vmcnt(16)
	ds_write_b128 v147, v[38:41] offset:34816
	v_lshl_add_u32 v147, v106, 1, s11
	s_waitcnt vmcnt(15)
	ds_write_b128 v147, v[42:45]
	s_waitcnt vmcnt(14)
	ds_write_b128 v147, v[46:49] offset:17408
	s_waitcnt vmcnt(13)
	ds_write_b128 v147, v[50:53] offset:34816
	v_lshl_add_u32 v147, v108, 1, s11
	s_waitcnt vmcnt(12)
	ds_write_b128 v147, v[54:57]
	s_waitcnt vmcnt(11)
	ds_write_b128 v147, v[58:61] offset:17408
	s_waitcnt vmcnt(10)
	ds_write_b128 v147, v[62:65] offset:34816
	v_lshl_add_u32 v147, v109, 1, s11
	v_add_u32_e32 v150, v147, v130
	v_add_u32_e32 v147, v147, v131
	s_waitcnt vmcnt(9)
	ds_write_b128 v150, v[70:73] offset:52224
	s_waitcnt vmcnt(8)
	ds_write_b128 v147, v[74:77] offset:52224
	s_and_saveexec_b64 s[8:9], s[0:1]
	v_add_u32_e32 v147, s11, v137
	ds_write_b128 v147, v[78:81] offset:61440
	s_or_b64 exec, exec, s[8:9]
	s_cmp_gt_u32 s10, 30
	s_cbranch_scc1 .LBB0_1301
	v_lshl_add_u64 v[26:27], v[120:121], 0, s[6:7]
	v_add_co_u32_e32 v18, vcc, 0x5740000, v26
	v_lshl_add_u64 v[34:35], v[118:119], 0, s[6:7]
	s_nop 0
	v_addc_co_u32_e32 v19, vcc, 0, v27, vcc
	v_add_co_u32_e32 v22, vcc, 0x7740000, v26
	s_mov_b32 s8, 0x5740000
	s_nop 0
	v_addc_co_u32_e32 v23, vcc, 0, v27, vcc
	v_add_co_u32_e32 v26, vcc, 0x9740000, v26
	v_lshl_add_u64 v[50:51], v[116:117], 0, s[6:7]
	s_nop 0
	v_addc_co_u32_e32 v27, vcc, 0, v27, vcc
	v_add_co_u32_e32 v30, vcc, s8, v34
	v_lshl_add_u64 v[58:59], v[114:115], 0, s[6:7]
	s_nop 0
	v_addc_co_u32_e32 v31, vcc, 0, v35, vcc
	v_add_co_u32_e32 v36, vcc, 0x7740000, v34
	global_load_dwordx4 v[18:21], v[18:19], off nt
	s_nop 0
	global_load_dwordx4 v[22:25], v[22:23], off nt
	v_addc_co_u32_e32 v37, vcc, 0, v35, vcc
	v_add_co_u32_e32 v38, vcc, 0x9740000, v34
	global_load_dwordx4 v[26:29], v[26:27], off nt
	s_nop 0
	global_load_dwordx4 v[30:33], v[30:31], off nt
	v_addc_co_u32_e32 v39, vcc, 0, v35, vcc
	v_add_co_u32_e32 v42, vcc, s8, v50
	global_load_dwordx4 v[34:37], v[36:37], off nt
	s_nop 0
	global_load_dwordx4 v[38:41], v[38:39], off nt
	v_addc_co_u32_e32 v43, vcc, 0, v51, vcc
	v_add_co_u32_e32 v46, vcc, 0x7740000, v50
	v_mov_b32_e32 v81, 0
	s_nop 0
	v_addc_co_u32_e32 v47, vcc, 0, v51, vcc
	v_add_co_u32_e32 v50, vcc, 0x9740000, v50
	global_load_dwordx4 v[42:45], v[42:43], off nt
	s_nop 0
	global_load_dwordx4 v[46:49], v[46:47], off nt
	v_addc_co_u32_e32 v51, vcc, 0, v51, vcc
	v_add_co_u32_e32 v54, vcc, s8, v58
	s_add_i32 s8, s15, s10
	s_nop 0
	v_addc_co_u32_e32 v55, vcc, 0, v59, vcc
	s_ashr_i32 s9, s8, 31
	v_add_co_u32_e32 v60, vcc, 0x7740000, v58
	s_lshl_b64 s[10:11], s[8:9], 13
	s_nop 0
	v_addc_co_u32_e32 v61, vcc, 0, v59, vcc
	s_add_u32 s10, s80, s10
	v_add_co_u32_e32 v62, vcc, 0x9740000, v58
	s_addc_u32 s11, s81, s11
	s_nop 0
	v_addc_co_u32_e32 v63, vcc, 0, v59, vcc
	v_lshl_add_u64 v[70:71], v[98:99], 1, s[10:11]
	v_lshl_add_u64 v[74:75], v[100:101], 1, s[10:11]
	global_load_dwordx4 v[50:53], v[50:51], off nt
	s_nop 0
	global_load_dwordx4 v[54:57], v[54:55], off nt
	s_nop 0
	global_load_dwordx4 v[58:61], v[60:61], off nt
	s_nop 0
	global_load_dwordx4 v[62:65], v[62:63], off nt
	s_nop 0
	global_load_dwordx4 v[70:73], v[70:71], off nt
	s_nop 0
	global_load_dwordx4 v[74:77], v[74:75], off nt
	v_mov_b32_e32 v80, 0
	v_mov_b32_e32 v79, 0
	v_mov_b32_e32 v78, 0
	s_and_saveexec_b64 s[10:11], s[0:1]
	s_cbranch_execz .LBB0_1300
	s_lshl_b64 s[8:9], s[8:9], 9
	v_lshl_add_u64 v[78:79], v[112:113], 0, s[8:9]
	global_load_dwordx4 v[78:81], v[78:79], off nt
